# pool_rows rewritten by hand: one block of 16 consecutive rows per wave, 31 rows loaded once, nested prefix window sums with packed f32 adds
# speedup vs baseline: 1.0144x; 1.0144x over previous
.Lcv_done:
.LBB0_362:
	s_cmp_lt_i32 s46, 0x8000
	s_cselect_b64 s[0:1], -1, 0
	s_cmpk_gt_i32 s46, 0x7fff
	v_lshrrev_b32_e32 v38, 4, v246
	s_cbranch_scc1 .LBB0_395
	v_lshlrev_b32_e32 v88, 3, v246
	v_lshrrev_b32_e32 v90, 4, v246
	v_cmp_le_u32_e64 s[72:73], 16, v246
	v_cmp_le_u32_e64 s[74:75], 32, v246
	v_cmp_le_u32_e64 s[76:77], 48, v246
	v_lshlrev_b32_e64 v91, v90, 2
	v_sub_u32_e32 v93, 0, v90
	v_ldexp_f32 v92, 0.5, v93
	s_lshl_b32 s2, s46, 4
	s_and_b32 s45, s2, 0xfff
	s_sub_i32 s24, s2, 15
	s_ashr_i32 s25, s24, 31
	s_lshl_b64 s[24:25], s[24:25], 9
	s_add_u32 s6, s68, s24
	s_addc_u32 s7, s69, s25
	s_cmp_eq_u32 s45, 0
	s_cbranch_scc1 .Lpool_first
	global_load_dwordx2 v[0:1], v88, s[6:7] offset:0
	global_load_dwordx2 v[2:3], v88, s[6:7] offset:512
	global_load_dwordx2 v[4:5], v88, s[6:7] offset:1024
	global_load_dwordx2 v[6:7], v88, s[6:7] offset:1536
	global_load_dwordx2 v[8:9], v88, s[6:7] offset:2048
	global_load_dwordx2 v[10:11], v88, s[6:7] offset:2560
	global_load_dwordx2 v[12:13], v88, s[6:7] offset:3072
	global_load_dwordx2 v[14:15], v88, s[6:7] offset:3584
	s_add_u32 s6, s6, 0x1000
	s_addc_u32 s7, s7, 0
	global_load_dwordx2 v[16:17], v88, s[6:7] offset:0
	global_load_dwordx2 v[18:19], v88, s[6:7] offset:512
	global_load_dwordx2 v[20:21], v88, s[6:7] offset:1024
	global_load_dwordx2 v[22:23], v88, s[6:7] offset:1536
	global_load_dwordx2 v[24:25], v88, s[6:7] offset:2048
	global_load_dwordx2 v[26:27], v88, s[6:7] offset:2560
	global_load_dwordx2 v[28:29], v88, s[6:7] offset:3072
	global_load_dwordx2 v[30:31], v88, s[6:7] offset:3584
	s_add_u32 s6, s6, 0x1000
	s_addc_u32 s7, s7, 0
	global_load_dwordx2 v[32:33], v88, s[6:7] offset:0
	global_load_dwordx2 v[34:35], v88, s[6:7] offset:512
	global_load_dwordx2 v[36:37], v88, s[6:7] offset:1024
	global_load_dwordx2 v[38:39], v88, s[6:7] offset:1536
	global_load_dwordx2 v[40:41], v88, s[6:7] offset:2048
	global_load_dwordx2 v[42:43], v88, s[6:7] offset:2560
	global_load_dwordx2 v[44:45], v88, s[6:7] offset:3072
	global_load_dwordx2 v[46:47], v88, s[6:7] offset:3584
	s_add_u32 s6, s6, 0x1000
	s_addc_u32 s7, s7, 0
	global_load_dwordx2 v[48:49], v88, s[6:7] offset:0
	global_load_dwordx2 v[50:51], v88, s[6:7] offset:512
	global_load_dwordx2 v[52:53], v88, s[6:7] offset:1024
	global_load_dwordx2 v[54:55], v88, s[6:7] offset:1536
	global_load_dwordx2 v[56:57], v88, s[6:7] offset:2048
	global_load_dwordx2 v[58:59], v88, s[6:7] offset:2560
	global_load_dwordx2 v[60:61], v88, s[6:7] offset:3072
	v_mov_b32_e32 v64, v92
	v_mov_b32_e32 v65, v92
	v_mov_b32_e32 v66, v92
	v_mov_b32_e32 v67, v92
	v_mov_b32_e32 v68, v92
	v_mov_b32_e32 v69, v92
	v_mov_b32_e32 v70, v92
	v_mov_b32_e32 v71, v92
	v_mov_b32_e32 v72, v92
	v_mov_b32_e32 v73, v92
	v_mov_b32_e32 v74, v92
	v_mov_b32_e32 v75, v92
	v_mov_b32_e32 v76, v92
	v_mov_b32_e32 v77, v92
	v_mov_b32_e32 v78, v92
	v_mov_b32_e32 v79, v92
	s_branch .Lpool_go
.Lpool_first:
	s_add_u32 s6, s6, 0x1000
	s_addc_u32 s7, s7, 0
	global_load_dwordx2 v[30:31], v88, s[6:7] offset:3584
	s_add_u32 s6, s6, 0x1000
	s_addc_u32 s7, s7, 0
	global_load_dwordx2 v[32:33], v88, s[6:7] offset:0
	global_load_dwordx2 v[34:35], v88, s[6:7] offset:512
	global_load_dwordx2 v[36:37], v88, s[6:7] offset:1024
	global_load_dwordx2 v[38:39], v88, s[6:7] offset:1536
	global_load_dwordx2 v[40:41], v88, s[6:7] offset:2048
	global_load_dwordx2 v[42:43], v88, s[6:7] offset:2560
	global_load_dwordx2 v[44:45], v88, s[6:7] offset:3072
	global_load_dwordx2 v[46:47], v88, s[6:7] offset:3584
	s_add_u32 s6, s6, 0x1000
	s_addc_u32 s7, s7, 0
	global_load_dwordx2 v[48:49], v88, s[6:7] offset:0
	global_load_dwordx2 v[50:51], v88, s[6:7] offset:512
	global_load_dwordx2 v[52:53], v88, s[6:7] offset:1024
	global_load_dwordx2 v[54:55], v88, s[6:7] offset:1536
	global_load_dwordx2 v[56:57], v88, s[6:7] offset:2048
	global_load_dwordx2 v[58:59], v88, s[6:7] offset:2560
	global_load_dwordx2 v[60:61], v88, s[6:7] offset:3072
	v_mov_b32_e32 v0, 0
	v_mov_b32_e32 v1, 0
	v_mov_b32_e32 v2, 0
	v_mov_b32_e32 v3, 0
	v_mov_b32_e32 v4, 0
	v_mov_b32_e32 v5, 0
	v_mov_b32_e32 v6, 0
	v_mov_b32_e32 v7, 0
	v_mov_b32_e32 v8, 0
	v_mov_b32_e32 v9, 0
	v_mov_b32_e32 v10, 0
	v_mov_b32_e32 v11, 0
	v_mov_b32_e32 v12, 0
	v_mov_b32_e32 v13, 0
	v_mov_b32_e32 v14, 0
	v_mov_b32_e32 v15, 0
	v_mov_b32_e32 v16, 0
	v_mov_b32_e32 v17, 0
	v_mov_b32_e32 v18, 0
	v_mov_b32_e32 v19, 0
	v_mov_b32_e32 v20, 0
	v_mov_b32_e32 v21, 0
	v_mov_b32_e32 v22, 0
	v_mov_b32_e32 v23, 0
	v_mov_b32_e32 v24, 0
	v_mov_b32_e32 v25, 0
	v_mov_b32_e32 v26, 0
	v_mov_b32_e32 v27, 0
	v_mov_b32_e32 v28, 0
	v_mov_b32_e32 v29, 0
	v_cmp_ge_u32_e32 vcc, 1, v91
	v_mov_b32_e32 v93, 0x3f800000
	s_nop 1
	v_cndmask_b32_e32 v64, v93, v92, vcc
	v_cmp_ge_u32_e32 vcc, 2, v91
	v_mov_b32_e32 v93, 0x3f000000
	s_nop 1
	v_cndmask_b32_e32 v65, v93, v92, vcc
	v_cmp_ge_u32_e32 vcc, 3, v91
	v_mov_b32_e32 v93, 0x3eaaaaab
	s_nop 1
	v_cndmask_b32_e32 v66, v93, v92, vcc
	v_cmp_ge_u32_e32 vcc, 4, v91
	v_mov_b32_e32 v93, 0x3e800000
	s_nop 1
	v_cndmask_b32_e32 v67, v93, v92, vcc
	v_cmp_ge_u32_e32 vcc, 5, v91
	v_mov_b32_e32 v93, 0x3e4ccccd
	s_nop 1
	v_cndmask_b32_e32 v68, v93, v92, vcc
	v_cmp_ge_u32_e32 vcc, 6, v91
	v_mov_b32_e32 v93, 0x3e2aaaab
	s_nop 1
	v_cndmask_b32_e32 v69, v93, v92, vcc
	v_cmp_ge_u32_e32 vcc, 7, v91
	v_mov_b32_e32 v93, 0x3e124925
	s_nop 1
	v_cndmask_b32_e32 v70, v93, v92, vcc
	v_cmp_ge_u32_e32 vcc, 8, v91
	v_mov_b32_e32 v93, 0x3e000000
	s_nop 1
	v_cndmask_b32_e32 v71, v93, v92, vcc
	v_cmp_ge_u32_e32 vcc, 9, v91
	v_mov_b32_e32 v93, 0x3de38e39
	s_nop 1
	v_cndmask_b32_e32 v72, v93, v92, vcc
	v_cmp_ge_u32_e32 vcc, 10, v91
	v_mov_b32_e32 v93, 0x3dcccccd
	s_nop 1
	v_cndmask_b32_e32 v73, v93, v92, vcc
	v_cmp_ge_u32_e32 vcc, 11, v91
	v_mov_b32_e32 v93, 0x3dba2e8c
	s_nop 1
	v_cndmask_b32_e32 v74, v93, v92, vcc
	v_cmp_ge_u32_e32 vcc, 12, v91
	v_mov_b32_e32 v93, 0x3daaaaab
	s_nop 1
	v_cndmask_b32_e32 v75, v93, v92, vcc
	v_cmp_ge_u32_e32 vcc, 13, v91
	v_mov_b32_e32 v93, 0x3d9d89d9
	s_nop 1
	v_cndmask_b32_e32 v76, v93, v92, vcc
	v_cmp_ge_u32_e32 vcc, 14, v91
	v_mov_b32_e32 v93, 0x3d924925
	s_nop 1
	v_cndmask_b32_e32 v77, v93, v92, vcc
	v_cmp_ge_u32_e32 vcc, 15, v91
	v_mov_b32_e32 v93, 0x3d888889
	s_nop 1
	v_cndmask_b32_e32 v78, v93, v92, vcc
	v_mov_b32_e32 v79, v92
.Lpool_go:
	s_lshl_b32 s24, s2, 11
	s_add_u32 s24, s24, 0x8600400
	s_add_u32 s24, s48, s24
	s_addc_u32 s25, s49, 0
	v_mov_b32_e32 v89, v88
	s_waitcnt vmcnt(0)
	v_lshlrev_b32_e32 v100, 16, v0
	v_and_b32_e32 v101, 0xffff0000, v0
	v_lshlrev_b32_e32 v102, 16, v1
	v_and_b32_e32 v103, 0xffff0000, v1
	v_lshlrev_b32_e32 v104, 16, v2
	v_and_b32_e32 v105, 0xffff0000, v2
	v_lshlrev_b32_e32 v106, 16, v3
	v_and_b32_e32 v107, 0xffff0000, v3
	v_lshlrev_b32_e32 v108, 16, v4
	v_and_b32_e32 v109, 0xffff0000, v4
	v_lshlrev_b32_e32 v110, 16, v5
	v_and_b32_e32 v111, 0xffff0000, v5
	v_lshlrev_b32_e32 v112, 16, v6
	v_and_b32_e32 v113, 0xffff0000, v6
	v_lshlrev_b32_e32 v114, 16, v7
	v_and_b32_e32 v115, 0xffff0000, v7
	v_lshlrev_b32_e32 v116, 16, v8
	v_and_b32_e32 v117, 0xffff0000, v8
	v_lshlrev_b32_e32 v118, 16, v9
	v_and_b32_e32 v119, 0xffff0000, v9
	v_lshlrev_b32_e32 v120, 16, v10
	v_and_b32_e32 v121, 0xffff0000, v10
	v_lshlrev_b32_e32 v122, 16, v11
	v_and_b32_e32 v123, 0xffff0000, v11
	v_lshlrev_b32_e32 v124, 16, v12
	v_and_b32_e32 v125, 0xffff0000, v12
	v_lshlrev_b32_e32 v126, 16, v13
	v_and_b32_e32 v127, 0xffff0000, v13
	v_lshlrev_b32_e32 v128, 16, v14
	v_and_b32_e32 v129, 0xffff0000, v14
	v_lshlrev_b32_e32 v130, 16, v15
	v_and_b32_e32 v131, 0xffff0000, v15
	v_lshlrev_b32_e32 v132, 16, v16
	v_and_b32_e32 v133, 0xffff0000, v16
	v_lshlrev_b32_e32 v134, 16, v17
	v_and_b32_e32 v135, 0xffff0000, v17
	v_lshlrev_b32_e32 v136, 16, v18
	v_and_b32_e32 v137, 0xffff0000, v18
	v_lshlrev_b32_e32 v138, 16, v19
	v_and_b32_e32 v139, 0xffff0000, v19
	v_lshlrev_b32_e32 v140, 16, v20
	v_and_b32_e32 v141, 0xffff0000, v20
	v_lshlrev_b32_e32 v142, 16, v21
	v_and_b32_e32 v143, 0xffff0000, v21
	v_lshlrev_b32_e32 v144, 16, v22
	v_and_b32_e32 v145, 0xffff0000, v22
	v_lshlrev_b32_e32 v146, 16, v23
	v_and_b32_e32 v147, 0xffff0000, v23
	v_lshlrev_b32_e32 v148, 16, v24
	v_and_b32_e32 v149, 0xffff0000, v24
	v_lshlrev_b32_e32 v150, 16, v25
	v_and_b32_e32 v151, 0xffff0000, v25
	v_lshlrev_b32_e32 v152, 16, v26
	v_and_b32_e32 v153, 0xffff0000, v26
	v_lshlrev_b32_e32 v154, 16, v27
	v_and_b32_e32 v155, 0xffff0000, v27
	v_lshlrev_b32_e32 v156, 16, v28
	v_and_b32_e32 v157, 0xffff0000, v28
	v_lshlrev_b32_e32 v158, 16, v29
	v_and_b32_e32 v159, 0xffff0000, v29
	v_lshlrev_b32_e32 v160, 16, v30
	v_and_b32_e32 v161, 0xffff0000, v30
	v_lshlrev_b32_e32 v162, 16, v31
	v_and_b32_e32 v163, 0xffff0000, v31
	v_lshlrev_b32_e32 v164, 16, v32
	v_and_b32_e32 v165, 0xffff0000, v32
	v_lshlrev_b32_e32 v166, 16, v33
	v_and_b32_e32 v167, 0xffff0000, v33
	v_lshlrev_b32_e32 v168, 16, v34
	v_and_b32_e32 v169, 0xffff0000, v34
	v_lshlrev_b32_e32 v170, 16, v35
	v_and_b32_e32 v171, 0xffff0000, v35
	v_lshlrev_b32_e32 v172, 16, v36
	v_and_b32_e32 v173, 0xffff0000, v36
	v_lshlrev_b32_e32 v174, 16, v37
	v_and_b32_e32 v175, 0xffff0000, v37
	v_lshlrev_b32_e32 v176, 16, v38
	v_and_b32_e32 v177, 0xffff0000, v38
	v_lshlrev_b32_e32 v178, 16, v39
	v_and_b32_e32 v179, 0xffff0000, v39
	v_lshlrev_b32_e32 v180, 16, v40
	v_and_b32_e32 v181, 0xffff0000, v40
	v_lshlrev_b32_e32 v182, 16, v41
	v_and_b32_e32 v183, 0xffff0000, v41
	v_lshlrev_b32_e32 v184, 16, v42
	v_and_b32_e32 v185, 0xffff0000, v42
	v_lshlrev_b32_e32 v186, 16, v43
	v_and_b32_e32 v187, 0xffff0000, v43
	v_lshlrev_b32_e32 v188, 16, v44
	v_and_b32_e32 v189, 0xffff0000, v44
	v_lshlrev_b32_e32 v190, 16, v45
	v_and_b32_e32 v191, 0xffff0000, v45
	v_lshlrev_b32_e32 v192, 16, v46
	v_and_b32_e32 v193, 0xffff0000, v46
	v_lshlrev_b32_e32 v194, 16, v47
	v_and_b32_e32 v195, 0xffff0000, v47
	v_lshlrev_b32_e32 v196, 16, v48
	v_and_b32_e32 v197, 0xffff0000, v48
	v_lshlrev_b32_e32 v198, 16, v49
	v_and_b32_e32 v199, 0xffff0000, v49
	v_lshlrev_b32_e32 v200, 16, v50
	v_and_b32_e32 v201, 0xffff0000, v50
	v_lshlrev_b32_e32 v202, 16, v51
	v_and_b32_e32 v203, 0xffff0000, v51
	v_lshlrev_b32_e32 v204, 16, v52
	v_and_b32_e32 v205, 0xffff0000, v52
	v_lshlrev_b32_e32 v206, 16, v53
	v_and_b32_e32 v207, 0xffff0000, v53
	v_lshlrev_b32_e32 v208, 16, v54
	v_and_b32_e32 v209, 0xffff0000, v54
	v_lshlrev_b32_e32 v210, 16, v55
	v_and_b32_e32 v211, 0xffff0000, v55
	v_lshlrev_b32_e32 v212, 16, v56
	v_and_b32_e32 v213, 0xffff0000, v56
	v_lshlrev_b32_e32 v214, 16, v57
	v_and_b32_e32 v215, 0xffff0000, v57
	v_lshlrev_b32_e32 v216, 16, v58
	v_and_b32_e32 v217, 0xffff0000, v58
	v_lshlrev_b32_e32 v218, 16, v59
	v_and_b32_e32 v219, 0xffff0000, v59
	v_lshlrev_b32_e32 v220, 16, v60
	v_and_b32_e32 v221, 0xffff0000, v60
	v_lshlrev_b32_e32 v222, 16, v61
	v_and_b32_e32 v223, 0xffff0000, v61
	v_pk_add_f32 v[80:81], v[160:161], v[156:157]
	v_pk_add_f32 v[82:83], v[162:163], v[158:159]
	v_mov_b32_e32 v84, v80
	v_mov_b32_e32 v85, v81
	v_mov_b32_e32 v86, v82
	v_mov_b32_e32 v87, v83
	v_pk_add_f32 v[80:81], v[80:81], v[152:153]
	v_pk_add_f32 v[82:83], v[82:83], v[154:155]
	v_pk_add_f32 v[80:81], v[80:81], v[148:149]
	v_pk_add_f32 v[82:83], v[82:83], v[150:151]
	v_cndmask_b32_e64 v84, v84, v80, s[72:73]
	v_cndmask_b32_e64 v85, v85, v81, s[72:73]
	v_cndmask_b32_e64 v86, v86, v82, s[72:73]
	v_cndmask_b32_e64 v87, v87, v83, s[72:73]
	v_pk_add_f32 v[80:81], v[80:81], v[144:145]
	v_pk_add_f32 v[82:83], v[82:83], v[146:147]
	v_pk_add_f32 v[80:81], v[80:81], v[140:141]
	v_pk_add_f32 v[82:83], v[82:83], v[142:143]
	v_pk_add_f32 v[80:81], v[80:81], v[136:137]
	v_pk_add_f32 v[82:83], v[82:83], v[138:139]
	v_pk_add_f32 v[80:81], v[80:81], v[132:133]
	v_pk_add_f32 v[82:83], v[82:83], v[134:135]
	v_cndmask_b32_e64 v84, v84, v80, s[74:75]
	v_cndmask_b32_e64 v85, v85, v81, s[74:75]
	v_cndmask_b32_e64 v86, v86, v82, s[74:75]
	v_cndmask_b32_e64 v87, v87, v83, s[74:75]
	v_pk_add_f32 v[80:81], v[80:81], v[128:129]
	v_pk_add_f32 v[82:83], v[82:83], v[130:131]
	v_pk_add_f32 v[80:81], v[80:81], v[124:125]
	v_pk_add_f32 v[82:83], v[82:83], v[126:127]
	v_pk_add_f32 v[80:81], v[80:81], v[120:121]
	v_pk_add_f32 v[82:83], v[82:83], v[122:123]
	v_pk_add_f32 v[80:81], v[80:81], v[116:117]
	v_pk_add_f32 v[82:83], v[82:83], v[118:119]
	v_pk_add_f32 v[80:81], v[80:81], v[112:113]
	v_pk_add_f32 v[82:83], v[82:83], v[114:115]
	v_pk_add_f32 v[80:81], v[80:81], v[108:109]
	v_pk_add_f32 v[82:83], v[82:83], v[110:111]
	v_pk_add_f32 v[80:81], v[80:81], v[104:105]
	v_pk_add_f32 v[82:83], v[82:83], v[106:107]
	v_pk_add_f32 v[80:81], v[80:81], v[100:101]
	v_pk_add_f32 v[82:83], v[82:83], v[102:103]
	v_cndmask_b32_e64 v84, v84, v80, s[76:77]
	v_cndmask_b32_e64 v85, v85, v81, s[76:77]
	v_cndmask_b32_e64 v86, v86, v82, s[76:77]
	v_cndmask_b32_e64 v87, v87, v83, s[76:77]
	v_fma_f32 v224, v64, v84, -v160
	v_fma_f32 v225, v64, v85, -v161
	v_fma_f32 v226, v64, v86, -v162
	v_fma_f32 v227, v64, v87, -v163
	v_cvt_pk_bf16_f32 v228, v224, v225
	v_cvt_pk_bf16_f32 v229, v226, v227
	global_store_dwordx2 v89, v[228:229], s[24:25] offset:0
	v_pk_add_f32 v[80:81], v[164:165], v[160:161]
	v_pk_add_f32 v[82:83], v[166:167], v[162:163]
	v_mov_b32_e32 v84, v80
	v_mov_b32_e32 v85, v81
	v_mov_b32_e32 v86, v82
	v_mov_b32_e32 v87, v83
	v_pk_add_f32 v[80:81], v[80:81], v[156:157]
	v_pk_add_f32 v[82:83], v[82:83], v[158:159]
	v_pk_add_f32 v[80:81], v[80:81], v[152:153]
	v_pk_add_f32 v[82:83], v[82:83], v[154:155]
	v_cndmask_b32_e64 v84, v84, v80, s[72:73]
	v_cndmask_b32_e64 v85, v85, v81, s[72:73]
	v_cndmask_b32_e64 v86, v86, v82, s[72:73]
	v_cndmask_b32_e64 v87, v87, v83, s[72:73]
	v_pk_add_f32 v[80:81], v[80:81], v[148:149]
	v_pk_add_f32 v[82:83], v[82:83], v[150:151]
	v_pk_add_f32 v[80:81], v[80:81], v[144:145]
	v_pk_add_f32 v[82:83], v[82:83], v[146:147]
	v_pk_add_f32 v[80:81], v[80:81], v[140:141]
	v_pk_add_f32 v[82:83], v[82:83], v[142:143]
	v_pk_add_f32 v[80:81], v[80:81], v[136:137]
	v_pk_add_f32 v[82:83], v[82:83], v[138:139]
	v_cndmask_b32_e64 v84, v84, v80, s[74:75]
	v_cndmask_b32_e64 v85, v85, v81, s[74:75]
	v_cndmask_b32_e64 v86, v86, v82, s[74:75]
	v_cndmask_b32_e64 v87, v87, v83, s[74:75]
	v_pk_add_f32 v[80:81], v[80:81], v[132:133]
	v_pk_add_f32 v[82:83], v[82:83], v[134:135]
	v_pk_add_f32 v[80:81], v[80:81], v[128:129]
	v_pk_add_f32 v[82:83], v[82:83], v[130:131]
	v_pk_add_f32 v[80:81], v[80:81], v[124:125]
	v_pk_add_f32 v[82:83], v[82:83], v[126:127]
	v_pk_add_f32 v[80:81], v[80:81], v[120:121]
	v_pk_add_f32 v[82:83], v[82:83], v[122:123]
	v_pk_add_f32 v[80:81], v[80:81], v[116:117]
	v_pk_add_f32 v[82:83], v[82:83], v[118:119]
	v_pk_add_f32 v[80:81], v[80:81], v[112:113]
	v_pk_add_f32 v[82:83], v[82:83], v[114:115]
	v_pk_add_f32 v[80:81], v[80:81], v[108:109]
	v_pk_add_f32 v[82:83], v[82:83], v[110:111]
	v_pk_add_f32 v[80:81], v[80:81], v[104:105]
	v_pk_add_f32 v[82:83], v[82:83], v[106:107]
	v_cndmask_b32_e64 v84, v84, v80, s[76:77]
	v_cndmask_b32_e64 v85, v85, v81, s[76:77]
	v_cndmask_b32_e64 v86, v86, v82, s[76:77]
	v_cndmask_b32_e64 v87, v87, v83, s[76:77]
	v_fma_f32 v224, v65, v84, -v164
	v_fma_f32 v225, v65, v85, -v165
	v_fma_f32 v226, v65, v86, -v166
	v_fma_f32 v227, v65, v87, -v167
	v_cvt_pk_bf16_f32 v230, v224, v225
	v_cvt_pk_bf16_f32 v231, v226, v227
	global_store_dwordx2 v89, v[230:231], s[24:25] offset:2048
	v_add_u32_e32 v89, 0x1000, v89
	v_pk_add_f32 v[80:81], v[168:169], v[164:165]
	v_pk_add_f32 v[82:83], v[170:171], v[166:167]
	v_mov_b32_e32 v84, v80
	v_mov_b32_e32 v85, v81
	v_mov_b32_e32 v86, v82
	v_mov_b32_e32 v87, v83
	v_pk_add_f32 v[80:81], v[80:81], v[160:161]
	v_pk_add_f32 v[82:83], v[82:83], v[162:163]
	v_pk_add_f32 v[80:81], v[80:81], v[156:157]
	v_pk_add_f32 v[82:83], v[82:83], v[158:159]
	v_cndmask_b32_e64 v84, v84, v80, s[72:73]
	v_cndmask_b32_e64 v85, v85, v81, s[72:73]
	v_cndmask_b32_e64 v86, v86, v82, s[72:73]
	v_cndmask_b32_e64 v87, v87, v83, s[72:73]
	v_pk_add_f32 v[80:81], v[80:81], v[152:153]
	v_pk_add_f32 v[82:83], v[82:83], v[154:155]
	v_pk_add_f32 v[80:81], v[80:81], v[148:149]
	v_pk_add_f32 v[82:83], v[82:83], v[150:151]
	v_pk_add_f32 v[80:81], v[80:81], v[144:145]
	v_pk_add_f32 v[82:83], v[82:83], v[146:147]
	v_pk_add_f32 v[80:81], v[80:81], v[140:141]
	v_pk_add_f32 v[82:83], v[82:83], v[142:143]
	v_cndmask_b32_e64 v84, v84, v80, s[74:75]
	v_cndmask_b32_e64 v85, v85, v81, s[74:75]
	v_cndmask_b32_e64 v86, v86, v82, s[74:75]
	v_cndmask_b32_e64 v87, v87, v83, s[74:75]
	v_pk_add_f32 v[80:81], v[80:81], v[136:137]
	v_pk_add_f32 v[82:83], v[82:83], v[138:139]
	v_pk_add_f32 v[80:81], v[80:81], v[132:133]
	v_pk_add_f32 v[82:83], v[82:83], v[134:135]
	v_pk_add_f32 v[80:81], v[80:81], v[128:129]
	v_pk_add_f32 v[82:83], v[82:83], v[130:131]
	v_pk_add_f32 v[80:81], v[80:81], v[124:125]
	v_pk_add_f32 v[82:83], v[82:83], v[126:127]
	v_pk_add_f32 v[80:81], v[80:81], v[120:121]
	v_pk_add_f32 v[82:83], v[82:83], v[122:123]
	v_pk_add_f32 v[80:81], v[80:81], v[116:117]
	v_pk_add_f32 v[82:83], v[82:83], v[118:119]
	v_pk_add_f32 v[80:81], v[80:81], v[112:113]
	v_pk_add_f32 v[82:83], v[82:83], v[114:115]
	v_pk_add_f32 v[80:81], v[80:81], v[108:109]
	v_pk_add_f32 v[82:83], v[82:83], v[110:111]
	v_cndmask_b32_e64 v84, v84, v80, s[76:77]
	v_cndmask_b32_e64 v85, v85, v81, s[76:77]
	v_cndmask_b32_e64 v86, v86, v82, s[76:77]
	v_cndmask_b32_e64 v87, v87, v83, s[76:77]
	v_fma_f32 v224, v66, v84, -v168
	v_fma_f32 v225, v66, v85, -v169
	v_fma_f32 v226, v66, v86, -v170
	v_fma_f32 v227, v66, v87, -v171
	v_cvt_pk_bf16_f32 v228, v224, v225
	v_cvt_pk_bf16_f32 v229, v226, v227
	global_store_dwordx2 v89, v[228:229], s[24:25] offset:0
	v_pk_add_f32 v[80:81], v[172:173], v[168:169]
	v_pk_add_f32 v[82:83], v[174:175], v[170:171]
	v_mov_b32_e32 v84, v80
	v_mov_b32_e32 v85, v81
	v_mov_b32_e32 v86, v82
	v_mov_b32_e32 v87, v83
	v_pk_add_f32 v[80:81], v[80:81], v[164:165]
	v_pk_add_f32 v[82:83], v[82:83], v[166:167]
	v_pk_add_f32 v[80:81], v[80:81], v[160:161]
	v_pk_add_f32 v[82:83], v[82:83], v[162:163]
	v_cndmask_b32_e64 v84, v84, v80, s[72:73]
	v_cndmask_b32_e64 v85, v85, v81, s[72:73]
	v_cndmask_b32_e64 v86, v86, v82, s[72:73]
	v_cndmask_b32_e64 v87, v87, v83, s[72:73]
	v_pk_add_f32 v[80:81], v[80:81], v[156:157]
	v_pk_add_f32 v[82:83], v[82:83], v[158:159]
	v_pk_add_f32 v[80:81], v[80:81], v[152:153]
	v_pk_add_f32 v[82:83], v[82:83], v[154:155]
	v_pk_add_f32 v[80:81], v[80:81], v[148:149]
	v_pk_add_f32 v[82:83], v[82:83], v[150:151]
	v_pk_add_f32 v[80:81], v[80:81], v[144:145]
	v_pk_add_f32 v[82:83], v[82:83], v[146:147]
	v_cndmask_b32_e64 v84, v84, v80, s[74:75]
	v_cndmask_b32_e64 v85, v85, v81, s[74:75]
	v_cndmask_b32_e64 v86, v86, v82, s[74:75]
	v_cndmask_b32_e64 v87, v87, v83, s[74:75]
	v_pk_add_f32 v[80:81], v[80:81], v[140:141]
	v_pk_add_f32 v[82:83], v[82:83], v[142:143]
	v_pk_add_f32 v[80:81], v[80:81], v[136:137]
	v_pk_add_f32 v[82:83], v[82:83], v[138:139]
	v_pk_add_f32 v[80:81], v[80:81], v[132:133]
	v_pk_add_f32 v[82:83], v[82:83], v[134:135]
	v_pk_add_f32 v[80:81], v[80:81], v[128:129]
	v_pk_add_f32 v[82:83], v[82:83], v[130:131]
	v_pk_add_f32 v[80:81], v[80:81], v[124:125]
	v_pk_add_f32 v[82:83], v[82:83], v[126:127]
	v_pk_add_f32 v[80:81], v[80:81], v[120:121]
	v_pk_add_f32 v[82:83], v[82:83], v[122:123]
	v_pk_add_f32 v[80:81], v[80:81], v[116:117]
	v_pk_add_f32 v[82:83], v[82:83], v[118:119]
	v_pk_add_f32 v[80:81], v[80:81], v[112:113]
	v_pk_add_f32 v[82:83], v[82:83], v[114:115]
	v_cndmask_b32_e64 v84, v84, v80, s[76:77]
	v_cndmask_b32_e64 v85, v85, v81, s[76:77]
	v_cndmask_b32_e64 v86, v86, v82, s[76:77]
	v_cndmask_b32_e64 v87, v87, v83, s[76:77]
	v_fma_f32 v224, v67, v84, -v172
	v_fma_f32 v225, v67, v85, -v173
	v_fma_f32 v226, v67, v86, -v174
	v_fma_f32 v227, v67, v87, -v175
	v_cvt_pk_bf16_f32 v230, v224, v225
	v_cvt_pk_bf16_f32 v231, v226, v227
	global_store_dwordx2 v89, v[230:231], s[24:25] offset:2048
	v_add_u32_e32 v89, 0x1000, v89
	v_pk_add_f32 v[80:81], v[176:177], v[172:173]
	v_pk_add_f32 v[82:83], v[178:179], v[174:175]
	v_mov_b32_e32 v84, v80
	v_mov_b32_e32 v85, v81
	v_mov_b32_e32 v86, v82
	v_mov_b32_e32 v87, v83
	v_pk_add_f32 v[80:81], v[80:81], v[168:169]
	v_pk_add_f32 v[82:83], v[82:83], v[170:171]
	v_pk_add_f32 v[80:81], v[80:81], v[164:165]
	v_pk_add_f32 v[82:83], v[82:83], v[166:167]
	v_cndmask_b32_e64 v84, v84, v80, s[72:73]
	v_cndmask_b32_e64 v85, v85, v81, s[72:73]
	v_cndmask_b32_e64 v86, v86, v82, s[72:73]
	v_cndmask_b32_e64 v87, v87, v83, s[72:73]
	v_pk_add_f32 v[80:81], v[80:81], v[160:161]
	v_pk_add_f32 v[82:83], v[82:83], v[162:163]
	v_pk_add_f32 v[80:81], v[80:81], v[156:157]
	v_pk_add_f32 v[82:83], v[82:83], v[158:159]
	v_pk_add_f32 v[80:81], v[80:81], v[152:153]
	v_pk_add_f32 v[82:83], v[82:83], v[154:155]
	v_pk_add_f32 v[80:81], v[80:81], v[148:149]
	v_pk_add_f32 v[82:83], v[82:83], v[150:151]
	v_cndmask_b32_e64 v84, v84, v80, s[74:75]
	v_cndmask_b32_e64 v85, v85, v81, s[74:75]
	v_cndmask_b32_e64 v86, v86, v82, s[74:75]
	v_cndmask_b32_e64 v87, v87, v83, s[74:75]
	v_pk_add_f32 v[80:81], v[80:81], v[144:145]
	v_pk_add_f32 v[82:83], v[82:83], v[146:147]
	v_pk_add_f32 v[80:81], v[80:81], v[140:141]
	v_pk_add_f32 v[82:83], v[82:83], v[142:143]
	v_pk_add_f32 v[80:81], v[80:81], v[136:137]
	v_pk_add_f32 v[82:83], v[82:83], v[138:139]
	v_pk_add_f32 v[80:81], v[80:81], v[132:133]
	v_pk_add_f32 v[82:83], v[82:83], v[134:135]
	v_pk_add_f32 v[80:81], v[80:81], v[128:129]
	v_pk_add_f32 v[82:83], v[82:83], v[130:131]
	v_pk_add_f32 v[80:81], v[80:81], v[124:125]
	v_pk_add_f32 v[82:83], v[82:83], v[126:127]
	v_pk_add_f32 v[80:81], v[80:81], v[120:121]
	v_pk_add_f32 v[82:83], v[82:83], v[122:123]
	v_pk_add_f32 v[80:81], v[80:81], v[116:117]
	v_pk_add_f32 v[82:83], v[82:83], v[118:119]
	v_cndmask_b32_e64 v84, v84, v80, s[76:77]
	v_cndmask_b32_e64 v85, v85, v81, s[76:77]
	v_cndmask_b32_e64 v86, v86, v82, s[76:77]
	v_cndmask_b32_e64 v87, v87, v83, s[76:77]
	v_fma_f32 v224, v68, v84, -v176
	v_fma_f32 v225, v68, v85, -v177
	v_fma_f32 v226, v68, v86, -v178
	v_fma_f32 v227, v68, v87, -v179
	v_cvt_pk_bf16_f32 v228, v224, v225
	v_cvt_pk_bf16_f32 v229, v226, v227
	global_store_dwordx2 v89, v[228:229], s[24:25] offset:0
	v_pk_add_f32 v[80:81], v[180:181], v[176:177]
	v_pk_add_f32 v[82:83], v[182:183], v[178:179]
	v_mov_b32_e32 v84, v80
	v_mov_b32_e32 v85, v81
	v_mov_b32_e32 v86, v82
	v_mov_b32_e32 v87, v83
	v_pk_add_f32 v[80:81], v[80:81], v[172:173]
	v_pk_add_f32 v[82:83], v[82:83], v[174:175]
	v_pk_add_f32 v[80:81], v[80:81], v[168:169]
	v_pk_add_f32 v[82:83], v[82:83], v[170:171]
	v_cndmask_b32_e64 v84, v84, v80, s[72:73]
	v_cndmask_b32_e64 v85, v85, v81, s[72:73]
	v_cndmask_b32_e64 v86, v86, v82, s[72:73]
	v_cndmask_b32_e64 v87, v87, v83, s[72:73]
	v_pk_add_f32 v[80:81], v[80:81], v[164:165]
	v_pk_add_f32 v[82:83], v[82:83], v[166:167]
	v_pk_add_f32 v[80:81], v[80:81], v[160:161]
	v_pk_add_f32 v[82:83], v[82:83], v[162:163]
	v_pk_add_f32 v[80:81], v[80:81], v[156:157]
	v_pk_add_f32 v[82:83], v[82:83], v[158:159]
	v_pk_add_f32 v[80:81], v[80:81], v[152:153]
	v_pk_add_f32 v[82:83], v[82:83], v[154:155]
	v_cndmask_b32_e64 v84, v84, v80, s[74:75]
	v_cndmask_b32_e64 v85, v85, v81, s[74:75]
	v_cndmask_b32_e64 v86, v86, v82, s[74:75]
	v_cndmask_b32_e64 v87, v87, v83, s[74:75]
	v_pk_add_f32 v[80:81], v[80:81], v[148:149]
	v_pk_add_f32 v[82:83], v[82:83], v[150:151]
	v_pk_add_f32 v[80:81], v[80:81], v[144:145]
	v_pk_add_f32 v[82:83], v[82:83], v[146:147]
	v_pk_add_f32 v[80:81], v[80:81], v[140:141]
	v_pk_add_f32 v[82:83], v[82:83], v[142:143]
	v_pk_add_f32 v[80:81], v[80:81], v[136:137]
	v_pk_add_f32 v[82:83], v[82:83], v[138:139]
	v_pk_add_f32 v[80:81], v[80:81], v[132:133]
	v_pk_add_f32 v[82:83], v[82:83], v[134:135]
	v_pk_add_f32 v[80:81], v[80:81], v[128:129]
	v_pk_add_f32 v[82:83], v[82:83], v[130:131]
	v_pk_add_f32 v[80:81], v[80:81], v[124:125]
	v_pk_add_f32 v[82:83], v[82:83], v[126:127]
	v_pk_add_f32 v[80:81], v[80:81], v[120:121]
	v_pk_add_f32 v[82:83], v[82:83], v[122:123]
	v_cndmask_b32_e64 v84, v84, v80, s[76:77]
	v_cndmask_b32_e64 v85, v85, v81, s[76:77]
	v_cndmask_b32_e64 v86, v86, v82, s[76:77]
	v_cndmask_b32_e64 v87, v87, v83, s[76:77]
	v_fma_f32 v224, v69, v84, -v180
	v_fma_f32 v225, v69, v85, -v181
	v_fma_f32 v226, v69, v86, -v182
	v_fma_f32 v227, v69, v87, -v183
	v_cvt_pk_bf16_f32 v230, v224, v225
	v_cvt_pk_bf16_f32 v231, v226, v227
	global_store_dwordx2 v89, v[230:231], s[24:25] offset:2048
	v_add_u32_e32 v89, 0x1000, v89
	v_pk_add_f32 v[80:81], v[184:185], v[180:181]
	v_pk_add_f32 v[82:83], v[186:187], v[182:183]
	v_mov_b32_e32 v84, v80
	v_mov_b32_e32 v85, v81
	v_mov_b32_e32 v86, v82
	v_mov_b32_e32 v87, v83
	v_pk_add_f32 v[80:81], v[80:81], v[176:177]
	v_pk_add_f32 v[82:83], v[82:83], v[178:179]
	v_pk_add_f32 v[80:81], v[80:81], v[172:173]
	v_pk_add_f32 v[82:83], v[82:83], v[174:175]
	v_cndmask_b32_e64 v84, v84, v80, s[72:73]
	v_cndmask_b32_e64 v85, v85, v81, s[72:73]
	v_cndmask_b32_e64 v86, v86, v82, s[72:73]
	v_cndmask_b32_e64 v87, v87, v83, s[72:73]
	v_pk_add_f32 v[80:81], v[80:81], v[168:169]
	v_pk_add_f32 v[82:83], v[82:83], v[170:171]
	v_pk_add_f32 v[80:81], v[80:81], v[164:165]
	v_pk_add_f32 v[82:83], v[82:83], v[166:167]
	v_pk_add_f32 v[80:81], v[80:81], v[160:161]
	v_pk_add_f32 v[82:83], v[82:83], v[162:163]
	v_pk_add_f32 v[80:81], v[80:81], v[156:157]
	v_pk_add_f32 v[82:83], v[82:83], v[158:159]
	v_cndmask_b32_e64 v84, v84, v80, s[74:75]
	v_cndmask_b32_e64 v85, v85, v81, s[74:75]
	v_cndmask_b32_e64 v86, v86, v82, s[74:75]
	v_cndmask_b32_e64 v87, v87, v83, s[74:75]
	v_pk_add_f32 v[80:81], v[80:81], v[152:153]
	v_pk_add_f32 v[82:83], v[82:83], v[154:155]
	v_pk_add_f32 v[80:81], v[80:81], v[148:149]
	v_pk_add_f32 v[82:83], v[82:83], v[150:151]
	v_pk_add_f32 v[80:81], v[80:81], v[144:145]
	v_pk_add_f32 v[82:83], v[82:83], v[146:147]
	v_pk_add_f32 v[80:81], v[80:81], v[140:141]
	v_pk_add_f32 v[82:83], v[82:83], v[142:143]
	v_pk_add_f32 v[80:81], v[80:81], v[136:137]
	v_pk_add_f32 v[82:83], v[82:83], v[138:139]
	v_pk_add_f32 v[80:81], v[80:81], v[132:133]
	v_pk_add_f32 v[82:83], v[82:83], v[134:135]
	v_pk_add_f32 v[80:81], v[80:81], v[128:129]
	v_pk_add_f32 v[82:83], v[82:83], v[130:131]
	v_pk_add_f32 v[80:81], v[80:81], v[124:125]
	v_pk_add_f32 v[82:83], v[82:83], v[126:127]
	v_cndmask_b32_e64 v84, v84, v80, s[76:77]
	v_cndmask_b32_e64 v85, v85, v81, s[76:77]
	v_cndmask_b32_e64 v86, v86, v82, s[76:77]
	v_cndmask_b32_e64 v87, v87, v83, s[76:77]
	v_fma_f32 v224, v70, v84, -v184
	v_fma_f32 v225, v70, v85, -v185
	v_fma_f32 v226, v70, v86, -v186
	v_fma_f32 v227, v70, v87, -v187
	v_cvt_pk_bf16_f32 v228, v224, v225
	v_cvt_pk_bf16_f32 v229, v226, v227
	global_store_dwordx2 v89, v[228:229], s[24:25] offset:0
	v_pk_add_f32 v[80:81], v[188:189], v[184:185]
	v_pk_add_f32 v[82:83], v[190:191], v[186:187]
	v_mov_b32_e32 v84, v80
	v_mov_b32_e32 v85, v81
	v_mov_b32_e32 v86, v82
	v_mov_b32_e32 v87, v83
	v_pk_add_f32 v[80:81], v[80:81], v[180:181]
	v_pk_add_f32 v[82:83], v[82:83], v[182:183]
	v_pk_add_f32 v[80:81], v[80:81], v[176:177]
	v_pk_add_f32 v[82:83], v[82:83], v[178:179]
	v_cndmask_b32_e64 v84, v84, v80, s[72:73]
	v_cndmask_b32_e64 v85, v85, v81, s[72:73]
	v_cndmask_b32_e64 v86, v86, v82, s[72:73]
	v_cndmask_b32_e64 v87, v87, v83, s[72:73]
	v_pk_add_f32 v[80:81], v[80:81], v[172:173]
	v_pk_add_f32 v[82:83], v[82:83], v[174:175]
	v_pk_add_f32 v[80:81], v[80:81], v[168:169]
	v_pk_add_f32 v[82:83], v[82:83], v[170:171]
	v_pk_add_f32 v[80:81], v[80:81], v[164:165]
	v_pk_add_f32 v[82:83], v[82:83], v[166:167]
	v_pk_add_f32 v[80:81], v[80:81], v[160:161]
	v_pk_add_f32 v[82:83], v[82:83], v[162:163]
	v_cndmask_b32_e64 v84, v84, v80, s[74:75]
	v_cndmask_b32_e64 v85, v85, v81, s[74:75]
	v_cndmask_b32_e64 v86, v86, v82, s[74:75]
	v_cndmask_b32_e64 v87, v87, v83, s[74:75]
	v_pk_add_f32 v[80:81], v[80:81], v[156:157]
	v_pk_add_f32 v[82:83], v[82:83], v[158:159]
	v_pk_add_f32 v[80:81], v[80:81], v[152:153]
	v_pk_add_f32 v[82:83], v[82:83], v[154:155]
	v_pk_add_f32 v[80:81], v[80:81], v[148:149]
	v_pk_add_f32 v[82:83], v[82:83], v[150:151]
	v_pk_add_f32 v[80:81], v[80:81], v[144:145]
	v_pk_add_f32 v[82:83], v[82:83], v[146:147]
	v_pk_add_f32 v[80:81], v[80:81], v[140:141]
	v_pk_add_f32 v[82:83], v[82:83], v[142:143]
	v_pk_add_f32 v[80:81], v[80:81], v[136:137]
	v_pk_add_f32 v[82:83], v[82:83], v[138:139]
	v_pk_add_f32 v[80:81], v[80:81], v[132:133]
	v_pk_add_f32 v[82:83], v[82:83], v[134:135]
	v_pk_add_f32 v[80:81], v[80:81], v[128:129]
	v_pk_add_f32 v[82:83], v[82:83], v[130:131]
	v_cndmask_b32_e64 v84, v84, v80, s[76:77]
	v_cndmask_b32_e64 v85, v85, v81, s[76:77]
	v_cndmask_b32_e64 v86, v86, v82, s[76:77]
	v_cndmask_b32_e64 v87, v87, v83, s[76:77]
	v_fma_f32 v224, v71, v84, -v188
	v_fma_f32 v225, v71, v85, -v189
	v_fma_f32 v226, v71, v86, -v190
	v_fma_f32 v227, v71, v87, -v191
	v_cvt_pk_bf16_f32 v230, v224, v225
	v_cvt_pk_bf16_f32 v231, v226, v227
	global_store_dwordx2 v89, v[230:231], s[24:25] offset:2048
	v_add_u32_e32 v89, 0x1000, v89
	v_pk_add_f32 v[80:81], v[192:193], v[188:189]
	v_pk_add_f32 v[82:83], v[194:195], v[190:191]
	v_mov_b32_e32 v84, v80
	v_mov_b32_e32 v85, v81
	v_mov_b32_e32 v86, v82
	v_mov_b32_e32 v87, v83
	v_pk_add_f32 v[80:81], v[80:81], v[184:185]
	v_pk_add_f32 v[82:83], v[82:83], v[186:187]
	v_pk_add_f32 v[80:81], v[80:81], v[180:181]
	v_pk_add_f32 v[82:83], v[82:83], v[182:183]
	v_cndmask_b32_e64 v84, v84, v80, s[72:73]
	v_cndmask_b32_e64 v85, v85, v81, s[72:73]
	v_cndmask_b32_e64 v86, v86, v82, s[72:73]
	v_cndmask_b32_e64 v87, v87, v83, s[72:73]
	v_pk_add_f32 v[80:81], v[80:81], v[176:177]
	v_pk_add_f32 v[82:83], v[82:83], v[178:179]
	v_pk_add_f32 v[80:81], v[80:81], v[172:173]
	v_pk_add_f32 v[82:83], v[82:83], v[174:175]
	v_pk_add_f32 v[80:81], v[80:81], v[168:169]
	v_pk_add_f32 v[82:83], v[82:83], v[170:171]
	v_pk_add_f32 v[80:81], v[80:81], v[164:165]
	v_pk_add_f32 v[82:83], v[82:83], v[166:167]
	v_cndmask_b32_e64 v84, v84, v80, s[74:75]
	v_cndmask_b32_e64 v85, v85, v81, s[74:75]
	v_cndmask_b32_e64 v86, v86, v82, s[74:75]
	v_cndmask_b32_e64 v87, v87, v83, s[74:75]
	v_pk_add_f32 v[80:81], v[80:81], v[160:161]
	v_pk_add_f32 v[82:83], v[82:83], v[162:163]
	v_pk_add_f32 v[80:81], v[80:81], v[156:157]
	v_pk_add_f32 v[82:83], v[82:83], v[158:159]
	v_pk_add_f32 v[80:81], v[80:81], v[152:153]
	v_pk_add_f32 v[82:83], v[82:83], v[154:155]
	v_pk_add_f32 v[80:81], v[80:81], v[148:149]
	v_pk_add_f32 v[82:83], v[82:83], v[150:151]
	v_pk_add_f32 v[80:81], v[80:81], v[144:145]
	v_pk_add_f32 v[82:83], v[82:83], v[146:147]
	v_pk_add_f32 v[80:81], v[80:81], v[140:141]
	v_pk_add_f32 v[82:83], v[82:83], v[142:143]
	v_pk_add_f32 v[80:81], v[80:81], v[136:137]
	v_pk_add_f32 v[82:83], v[82:83], v[138:139]
	v_pk_add_f32 v[80:81], v[80:81], v[132:133]
	v_pk_add_f32 v[82:83], v[82:83], v[134:135]
	v_cndmask_b32_e64 v84, v84, v80, s[76:77]
	v_cndmask_b32_e64 v85, v85, v81, s[76:77]
	v_cndmask_b32_e64 v86, v86, v82, s[76:77]
	v_cndmask_b32_e64 v87, v87, v83, s[76:77]
	v_fma_f32 v224, v72, v84, -v192
	v_fma_f32 v225, v72, v85, -v193
	v_fma_f32 v226, v72, v86, -v194
	v_fma_f32 v227, v72, v87, -v195
	v_cvt_pk_bf16_f32 v228, v224, v225
	v_cvt_pk_bf16_f32 v229, v226, v227
	global_store_dwordx2 v89, v[228:229], s[24:25] offset:0
	v_pk_add_f32 v[80:81], v[196:197], v[192:193]
	v_pk_add_f32 v[82:83], v[198:199], v[194:195]
	v_mov_b32_e32 v84, v80
	v_mov_b32_e32 v85, v81
	v_mov_b32_e32 v86, v82
	v_mov_b32_e32 v87, v83
	v_pk_add_f32 v[80:81], v[80:81], v[188:189]
	v_pk_add_f32 v[82:83], v[82:83], v[190:191]
	v_pk_add_f32 v[80:81], v[80:81], v[184:185]
	v_pk_add_f32 v[82:83], v[82:83], v[186:187]
	v_cndmask_b32_e64 v84, v84, v80, s[72:73]
	v_cndmask_b32_e64 v85, v85, v81, s[72:73]
	v_cndmask_b32_e64 v86, v86, v82, s[72:73]
	v_cndmask_b32_e64 v87, v87, v83, s[72:73]
	v_pk_add_f32 v[80:81], v[80:81], v[180:181]
	v_pk_add_f32 v[82:83], v[82:83], v[182:183]
	v_pk_add_f32 v[80:81], v[80:81], v[176:177]
	v_pk_add_f32 v[82:83], v[82:83], v[178:179]
	v_pk_add_f32 v[80:81], v[80:81], v[172:173]
	v_pk_add_f32 v[82:83], v[82:83], v[174:175]
	v_pk_add_f32 v[80:81], v[80:81], v[168:169]
	v_pk_add_f32 v[82:83], v[82:83], v[170:171]
	v_cndmask_b32_e64 v84, v84, v80, s[74:75]
	v_cndmask_b32_e64 v85, v85, v81, s[74:75]
	v_cndmask_b32_e64 v86, v86, v82, s[74:75]
	v_cndmask_b32_e64 v87, v87, v83, s[74:75]
	v_pk_add_f32 v[80:81], v[80:81], v[164:165]
	v_pk_add_f32 v[82:83], v[82:83], v[166:167]
	v_pk_add_f32 v[80:81], v[80:81], v[160:161]
	v_pk_add_f32 v[82:83], v[82:83], v[162:163]
	v_pk_add_f32 v[80:81], v[80:81], v[156:157]
	v_pk_add_f32 v[82:83], v[82:83], v[158:159]
	v_pk_add_f32 v[80:81], v[80:81], v[152:153]
	v_pk_add_f32 v[82:83], v[82:83], v[154:155]
	v_pk_add_f32 v[80:81], v[80:81], v[148:149]
	v_pk_add_f32 v[82:83], v[82:83], v[150:151]
	v_pk_add_f32 v[80:81], v[80:81], v[144:145]
	v_pk_add_f32 v[82:83], v[82:83], v[146:147]
	v_pk_add_f32 v[80:81], v[80:81], v[140:141]
	v_pk_add_f32 v[82:83], v[82:83], v[142:143]
	v_pk_add_f32 v[80:81], v[80:81], v[136:137]
	v_pk_add_f32 v[82:83], v[82:83], v[138:139]
	v_cndmask_b32_e64 v84, v84, v80, s[76:77]
	v_cndmask_b32_e64 v85, v85, v81, s[76:77]
	v_cndmask_b32_e64 v86, v86, v82, s[76:77]
	v_cndmask_b32_e64 v87, v87, v83, s[76:77]
	v_fma_f32 v224, v73, v84, -v196
	v_fma_f32 v225, v73, v85, -v197
	v_fma_f32 v226, v73, v86, -v198
	v_fma_f32 v227, v73, v87, -v199
	v_cvt_pk_bf16_f32 v230, v224, v225
	v_cvt_pk_bf16_f32 v231, v226, v227
	global_store_dwordx2 v89, v[230:231], s[24:25] offset:2048
	v_add_u32_e32 v89, 0x1000, v89
	v_pk_add_f32 v[80:81], v[200:201], v[196:197]
	v_pk_add_f32 v[82:83], v[202:203], v[198:199]
	v_mov_b32_e32 v84, v80
	v_mov_b32_e32 v85, v81
	v_mov_b32_e32 v86, v82
	v_mov_b32_e32 v87, v83
	v_pk_add_f32 v[80:81], v[80:81], v[192:193]
	v_pk_add_f32 v[82:83], v[82:83], v[194:195]
	v_pk_add_f32 v[80:81], v[80:81], v[188:189]
	v_pk_add_f32 v[82:83], v[82:83], v[190:191]
	v_cndmask_b32_e64 v84, v84, v80, s[72:73]
	v_cndmask_b32_e64 v85, v85, v81, s[72:73]
	v_cndmask_b32_e64 v86, v86, v82, s[72:73]
	v_cndmask_b32_e64 v87, v87, v83, s[72:73]
	v_pk_add_f32 v[80:81], v[80:81], v[184:185]
	v_pk_add_f32 v[82:83], v[82:83], v[186:187]
	v_pk_add_f32 v[80:81], v[80:81], v[180:181]
	v_pk_add_f32 v[82:83], v[82:83], v[182:183]
	v_pk_add_f32 v[80:81], v[80:81], v[176:177]
	v_pk_add_f32 v[82:83], v[82:83], v[178:179]
	v_pk_add_f32 v[80:81], v[80:81], v[172:173]
	v_pk_add_f32 v[82:83], v[82:83], v[174:175]
	v_cndmask_b32_e64 v84, v84, v80, s[74:75]
	v_cndmask_b32_e64 v85, v85, v81, s[74:75]
	v_cndmask_b32_e64 v86, v86, v82, s[74:75]
	v_cndmask_b32_e64 v87, v87, v83, s[74:75]
	v_pk_add_f32 v[80:81], v[80:81], v[168:169]
	v_pk_add_f32 v[82:83], v[82:83], v[170:171]
	v_pk_add_f32 v[80:81], v[80:81], v[164:165]
	v_pk_add_f32 v[82:83], v[82:83], v[166:167]
	v_pk_add_f32 v[80:81], v[80:81], v[160:161]
	v_pk_add_f32 v[82:83], v[82:83], v[162:163]
	v_pk_add_f32 v[80:81], v[80:81], v[156:157]
	v_pk_add_f32 v[82:83], v[82:83], v[158:159]
	v_pk_add_f32 v[80:81], v[80:81], v[152:153]
	v_pk_add_f32 v[82:83], v[82:83], v[154:155]
	v_pk_add_f32 v[80:81], v[80:81], v[148:149]
	v_pk_add_f32 v[82:83], v[82:83], v[150:151]
	v_pk_add_f32 v[80:81], v[80:81], v[144:145]
	v_pk_add_f32 v[82:83], v[82:83], v[146:147]
	v_pk_add_f32 v[80:81], v[80:81], v[140:141]
	v_pk_add_f32 v[82:83], v[82:83], v[142:143]
	v_cndmask_b32_e64 v84, v84, v80, s[76:77]
	v_cndmask_b32_e64 v85, v85, v81, s[76:77]
	v_cndmask_b32_e64 v86, v86, v82, s[76:77]
	v_cndmask_b32_e64 v87, v87, v83, s[76:77]
	v_fma_f32 v224, v74, v84, -v200
	v_fma_f32 v225, v74, v85, -v201
	v_fma_f32 v226, v74, v86, -v202
	v_fma_f32 v227, v74, v87, -v203
	v_cvt_pk_bf16_f32 v228, v224, v225
	v_cvt_pk_bf16_f32 v229, v226, v227
	global_store_dwordx2 v89, v[228:229], s[24:25] offset:0
	v_pk_add_f32 v[80:81], v[204:205], v[200:201]
	v_pk_add_f32 v[82:83], v[206:207], v[202:203]
	v_mov_b32_e32 v84, v80
	v_mov_b32_e32 v85, v81
	v_mov_b32_e32 v86, v82
	v_mov_b32_e32 v87, v83
	v_pk_add_f32 v[80:81], v[80:81], v[196:197]
	v_pk_add_f32 v[82:83], v[82:83], v[198:199]
	v_pk_add_f32 v[80:81], v[80:81], v[192:193]
	v_pk_add_f32 v[82:83], v[82:83], v[194:195]
	v_cndmask_b32_e64 v84, v84, v80, s[72:73]
	v_cndmask_b32_e64 v85, v85, v81, s[72:73]
	v_cndmask_b32_e64 v86, v86, v82, s[72:73]
	v_cndmask_b32_e64 v87, v87, v83, s[72:73]
	v_pk_add_f32 v[80:81], v[80:81], v[188:189]
	v_pk_add_f32 v[82:83], v[82:83], v[190:191]
	v_pk_add_f32 v[80:81], v[80:81], v[184:185]
	v_pk_add_f32 v[82:83], v[82:83], v[186:187]
	v_pk_add_f32 v[80:81], v[80:81], v[180:181]
	v_pk_add_f32 v[82:83], v[82:83], v[182:183]
	v_pk_add_f32 v[80:81], v[80:81], v[176:177]
	v_pk_add_f32 v[82:83], v[82:83], v[178:179]
	v_cndmask_b32_e64 v84, v84, v80, s[74:75]
	v_cndmask_b32_e64 v85, v85, v81, s[74:75]
	v_cndmask_b32_e64 v86, v86, v82, s[74:75]
	v_cndmask_b32_e64 v87, v87, v83, s[74:75]
	v_pk_add_f32 v[80:81], v[80:81], v[172:173]
	v_pk_add_f32 v[82:83], v[82:83], v[174:175]
	v_pk_add_f32 v[80:81], v[80:81], v[168:169]
	v_pk_add_f32 v[82:83], v[82:83], v[170:171]
	v_pk_add_f32 v[80:81], v[80:81], v[164:165]
	v_pk_add_f32 v[82:83], v[82:83], v[166:167]
	v_pk_add_f32 v[80:81], v[80:81], v[160:161]
	v_pk_add_f32 v[82:83], v[82:83], v[162:163]
	v_pk_add_f32 v[80:81], v[80:81], v[156:157]
	v_pk_add_f32 v[82:83], v[82:83], v[158:159]
	v_pk_add_f32 v[80:81], v[80:81], v[152:153]
	v_pk_add_f32 v[82:83], v[82:83], v[154:155]
	v_pk_add_f32 v[80:81], v[80:81], v[148:149]
	v_pk_add_f32 v[82:83], v[82:83], v[150:151]
	v_pk_add_f32 v[80:81], v[80:81], v[144:145]
	v_pk_add_f32 v[82:83], v[82:83], v[146:147]
	v_cndmask_b32_e64 v84, v84, v80, s[76:77]
	v_cndmask_b32_e64 v85, v85, v81, s[76:77]
	v_cndmask_b32_e64 v86, v86, v82, s[76:77]
	v_cndmask_b32_e64 v87, v87, v83, s[76:77]
	v_fma_f32 v224, v75, v84, -v204
	v_fma_f32 v225, v75, v85, -v205
	v_fma_f32 v226, v75, v86, -v206
	v_fma_f32 v227, v75, v87, -v207
	v_cvt_pk_bf16_f32 v230, v224, v225
	v_cvt_pk_bf16_f32 v231, v226, v227
	global_store_dwordx2 v89, v[230:231], s[24:25] offset:2048
	v_add_u32_e32 v89, 0x1000, v89
	v_pk_add_f32 v[80:81], v[208:209], v[204:205]
	v_pk_add_f32 v[82:83], v[210:211], v[206:207]
	v_mov_b32_e32 v84, v80
	v_mov_b32_e32 v85, v81
	v_mov_b32_e32 v86, v82
	v_mov_b32_e32 v87, v83
	v_pk_add_f32 v[80:81], v[80:81], v[200:201]
	v_pk_add_f32 v[82:83], v[82:83], v[202:203]
	v_pk_add_f32 v[80:81], v[80:81], v[196:197]
	v_pk_add_f32 v[82:83], v[82:83], v[198:199]
	v_cndmask_b32_e64 v84, v84, v80, s[72:73]
	v_cndmask_b32_e64 v85, v85, v81, s[72:73]
	v_cndmask_b32_e64 v86, v86, v82, s[72:73]
	v_cndmask_b32_e64 v87, v87, v83, s[72:73]
	v_pk_add_f32 v[80:81], v[80:81], v[192:193]
	v_pk_add_f32 v[82:83], v[82:83], v[194:195]
	v_pk_add_f32 v[80:81], v[80:81], v[188:189]
	v_pk_add_f32 v[82:83], v[82:83], v[190:191]
	v_pk_add_f32 v[80:81], v[80:81], v[184:185]
	v_pk_add_f32 v[82:83], v[82:83], v[186:187]
	v_pk_add_f32 v[80:81], v[80:81], v[180:181]
	v_pk_add_f32 v[82:83], v[82:83], v[182:183]
	v_cndmask_b32_e64 v84, v84, v80, s[74:75]
	v_cndmask_b32_e64 v85, v85, v81, s[74:75]
	v_cndmask_b32_e64 v86, v86, v82, s[74:75]
	v_cndmask_b32_e64 v87, v87, v83, s[74:75]
	v_pk_add_f32 v[80:81], v[80:81], v[176:177]
	v_pk_add_f32 v[82:83], v[82:83], v[178:179]
	v_pk_add_f32 v[80:81], v[80:81], v[172:173]
	v_pk_add_f32 v[82:83], v[82:83], v[174:175]
	v_pk_add_f32 v[80:81], v[80:81], v[168:169]
	v_pk_add_f32 v[82:83], v[82:83], v[170:171]
	v_pk_add_f32 v[80:81], v[80:81], v[164:165]
	v_pk_add_f32 v[82:83], v[82:83], v[166:167]
	v_pk_add_f32 v[80:81], v[80:81], v[160:161]
	v_pk_add_f32 v[82:83], v[82:83], v[162:163]
	v_pk_add_f32 v[80:81], v[80:81], v[156:157]
	v_pk_add_f32 v[82:83], v[82:83], v[158:159]
	v_pk_add_f32 v[80:81], v[80:81], v[152:153]
	v_pk_add_f32 v[82:83], v[82:83], v[154:155]
	v_pk_add_f32 v[80:81], v[80:81], v[148:149]
	v_pk_add_f32 v[82:83], v[82:83], v[150:151]
	v_cndmask_b32_e64 v84, v84, v80, s[76:77]
	v_cndmask_b32_e64 v85, v85, v81, s[76:77]
	v_cndmask_b32_e64 v86, v86, v82, s[76:77]
	v_cndmask_b32_e64 v87, v87, v83, s[76:77]
	v_fma_f32 v224, v76, v84, -v208
	v_fma_f32 v225, v76, v85, -v209
	v_fma_f32 v226, v76, v86, -v210
	v_fma_f32 v227, v76, v87, -v211
	v_cvt_pk_bf16_f32 v228, v224, v225
	v_cvt_pk_bf16_f32 v229, v226, v227
	global_store_dwordx2 v89, v[228:229], s[24:25] offset:0
	v_pk_add_f32 v[80:81], v[212:213], v[208:209]
	v_pk_add_f32 v[82:83], v[214:215], v[210:211]
	v_mov_b32_e32 v84, v80
	v_mov_b32_e32 v85, v81
	v_mov_b32_e32 v86, v82
	v_mov_b32_e32 v87, v83
	v_pk_add_f32 v[80:81], v[80:81], v[204:205]
	v_pk_add_f32 v[82:83], v[82:83], v[206:207]
	v_pk_add_f32 v[80:81], v[80:81], v[200:201]
	v_pk_add_f32 v[82:83], v[82:83], v[202:203]
	v_cndmask_b32_e64 v84, v84, v80, s[72:73]
	v_cndmask_b32_e64 v85, v85, v81, s[72:73]
	v_cndmask_b32_e64 v86, v86, v82, s[72:73]
	v_cndmask_b32_e64 v87, v87, v83, s[72:73]
	v_pk_add_f32 v[80:81], v[80:81], v[196:197]
	v_pk_add_f32 v[82:83], v[82:83], v[198:199]
	v_pk_add_f32 v[80:81], v[80:81], v[192:193]
	v_pk_add_f32 v[82:83], v[82:83], v[194:195]
	v_pk_add_f32 v[80:81], v[80:81], v[188:189]
	v_pk_add_f32 v[82:83], v[82:83], v[190:191]
	v_pk_add_f32 v[80:81], v[80:81], v[184:185]
	v_pk_add_f32 v[82:83], v[82:83], v[186:187]
	v_cndmask_b32_e64 v84, v84, v80, s[74:75]
	v_cndmask_b32_e64 v85, v85, v81, s[74:75]
	v_cndmask_b32_e64 v86, v86, v82, s[74:75]
	v_cndmask_b32_e64 v87, v87, v83, s[74:75]
	v_pk_add_f32 v[80:81], v[80:81], v[180:181]
	v_pk_add_f32 v[82:83], v[82:83], v[182:183]
	v_pk_add_f32 v[80:81], v[80:81], v[176:177]
	v_pk_add_f32 v[82:83], v[82:83], v[178:179]
	v_pk_add_f32 v[80:81], v[80:81], v[172:173]
	v_pk_add_f32 v[82:83], v[82:83], v[174:175]
	v_pk_add_f32 v[80:81], v[80:81], v[168:169]
	v_pk_add_f32 v[82:83], v[82:83], v[170:171]
	v_pk_add_f32 v[80:81], v[80:81], v[164:165]
	v_pk_add_f32 v[82:83], v[82:83], v[166:167]
	v_pk_add_f32 v[80:81], v[80:81], v[160:161]
	v_pk_add_f32 v[82:83], v[82:83], v[162:163]
	v_pk_add_f32 v[80:81], v[80:81], v[156:157]
	v_pk_add_f32 v[82:83], v[82:83], v[158:159]
	v_pk_add_f32 v[80:81], v[80:81], v[152:153]
	v_pk_add_f32 v[82:83], v[82:83], v[154:155]
	v_cndmask_b32_e64 v84, v84, v80, s[76:77]
	v_cndmask_b32_e64 v85, v85, v81, s[76:77]
	v_cndmask_b32_e64 v86, v86, v82, s[76:77]
	v_cndmask_b32_e64 v87, v87, v83, s[76:77]
	v_fma_f32 v224, v77, v84, -v212
	v_fma_f32 v225, v77, v85, -v213
	v_fma_f32 v226, v77, v86, -v214
	v_fma_f32 v227, v77, v87, -v215
	v_cvt_pk_bf16_f32 v230, v224, v225
	v_cvt_pk_bf16_f32 v231, v226, v227
	global_store_dwordx2 v89, v[230:231], s[24:25] offset:2048
	v_add_u32_e32 v89, 0x1000, v89
	v_pk_add_f32 v[80:81], v[216:217], v[212:213]
	v_pk_add_f32 v[82:83], v[218:219], v[214:215]
	v_mov_b32_e32 v84, v80
	v_mov_b32_e32 v85, v81
	v_mov_b32_e32 v86, v82
	v_mov_b32_e32 v87, v83
	v_pk_add_f32 v[80:81], v[80:81], v[208:209]
	v_pk_add_f32 v[82:83], v[82:83], v[210:211]
	v_pk_add_f32 v[80:81], v[80:81], v[204:205]
	v_pk_add_f32 v[82:83], v[82:83], v[206:207]
	v_cndmask_b32_e64 v84, v84, v80, s[72:73]
	v_cndmask_b32_e64 v85, v85, v81, s[72:73]
	v_cndmask_b32_e64 v86, v86, v82, s[72:73]
	v_cndmask_b32_e64 v87, v87, v83, s[72:73]
	v_pk_add_f32 v[80:81], v[80:81], v[200:201]
	v_pk_add_f32 v[82:83], v[82:83], v[202:203]
	v_pk_add_f32 v[80:81], v[80:81], v[196:197]
	v_pk_add_f32 v[82:83], v[82:83], v[198:199]
	v_pk_add_f32 v[80:81], v[80:81], v[192:193]
	v_pk_add_f32 v[82:83], v[82:83], v[194:195]
	v_pk_add_f32 v[80:81], v[80:81], v[188:189]
	v_pk_add_f32 v[82:83], v[82:83], v[190:191]
	v_cndmask_b32_e64 v84, v84, v80, s[74:75]
	v_cndmask_b32_e64 v85, v85, v81, s[74:75]
	v_cndmask_b32_e64 v86, v86, v82, s[74:75]
	v_cndmask_b32_e64 v87, v87, v83, s[74:75]
	v_pk_add_f32 v[80:81], v[80:81], v[184:185]
	v_pk_add_f32 v[82:83], v[82:83], v[186:187]
	v_pk_add_f32 v[80:81], v[80:81], v[180:181]
	v_pk_add_f32 v[82:83], v[82:83], v[182:183]
	v_pk_add_f32 v[80:81], v[80:81], v[176:177]
	v_pk_add_f32 v[82:83], v[82:83], v[178:179]
	v_pk_add_f32 v[80:81], v[80:81], v[172:173]
	v_pk_add_f32 v[82:83], v[82:83], v[174:175]
	v_pk_add_f32 v[80:81], v[80:81], v[168:169]
	v_pk_add_f32 v[82:83], v[82:83], v[170:171]
	v_pk_add_f32 v[80:81], v[80:81], v[164:165]
	v_pk_add_f32 v[82:83], v[82:83], v[166:167]
	v_pk_add_f32 v[80:81], v[80:81], v[160:161]
	v_pk_add_f32 v[82:83], v[82:83], v[162:163]
	v_pk_add_f32 v[80:81], v[80:81], v[156:157]
	v_pk_add_f32 v[82:83], v[82:83], v[158:159]
	v_cndmask_b32_e64 v84, v84, v80, s[76:77]
	v_cndmask_b32_e64 v85, v85, v81, s[76:77]
	v_cndmask_b32_e64 v86, v86, v82, s[76:77]
	v_cndmask_b32_e64 v87, v87, v83, s[76:77]
	v_fma_f32 v224, v78, v84, -v216
	v_fma_f32 v225, v78, v85, -v217
	v_fma_f32 v226, v78, v86, -v218
	v_fma_f32 v227, v78, v87, -v219
	v_cvt_pk_bf16_f32 v228, v224, v225
	v_cvt_pk_bf16_f32 v229, v226, v227
	global_store_dwordx2 v89, v[228:229], s[24:25] offset:0
	v_pk_add_f32 v[80:81], v[220:221], v[216:217]
	v_pk_add_f32 v[82:83], v[222:223], v[218:219]
	v_mov_b32_e32 v84, v80
	v_mov_b32_e32 v85, v81
	v_mov_b32_e32 v86, v82
	v_mov_b32_e32 v87, v83
	v_pk_add_f32 v[80:81], v[80:81], v[212:213]
	v_pk_add_f32 v[82:83], v[82:83], v[214:215]
	v_pk_add_f32 v[80:81], v[80:81], v[208:209]
	v_pk_add_f32 v[82:83], v[82:83], v[210:211]
	v_cndmask_b32_e64 v84, v84, v80, s[72:73]
	v_cndmask_b32_e64 v85, v85, v81, s[72:73]
	v_cndmask_b32_e64 v86, v86, v82, s[72:73]
	v_cndmask_b32_e64 v87, v87, v83, s[72:73]
	v_pk_add_f32 v[80:81], v[80:81], v[204:205]
	v_pk_add_f32 v[82:83], v[82:83], v[206:207]
	v_pk_add_f32 v[80:81], v[80:81], v[200:201]
	v_pk_add_f32 v[82:83], v[82:83], v[202:203]
	v_pk_add_f32 v[80:81], v[80:81], v[196:197]
	v_pk_add_f32 v[82:83], v[82:83], v[198:199]
	v_pk_add_f32 v[80:81], v[80:81], v[192:193]
	v_pk_add_f32 v[82:83], v[82:83], v[194:195]
	v_cndmask_b32_e64 v84, v84, v80, s[74:75]
	v_cndmask_b32_e64 v85, v85, v81, s[74:75]
	v_cndmask_b32_e64 v86, v86, v82, s[74:75]
	v_cndmask_b32_e64 v87, v87, v83, s[74:75]
	v_pk_add_f32 v[80:81], v[80:81], v[188:189]
	v_pk_add_f32 v[82:83], v[82:83], v[190:191]
	v_pk_add_f32 v[80:81], v[80:81], v[184:185]
	v_pk_add_f32 v[82:83], v[82:83], v[186:187]
	v_pk_add_f32 v[80:81], v[80:81], v[180:181]
	v_pk_add_f32 v[82:83], v[82:83], v[182:183]
	v_pk_add_f32 v[80:81], v[80:81], v[176:177]
	v_pk_add_f32 v[82:83], v[82:83], v[178:179]
	v_pk_add_f32 v[80:81], v[80:81], v[172:173]
	v_pk_add_f32 v[82:83], v[82:83], v[174:175]
	v_pk_add_f32 v[80:81], v[80:81], v[168:169]
	v_pk_add_f32 v[82:83], v[82:83], v[170:171]
	v_pk_add_f32 v[80:81], v[80:81], v[164:165]
	v_pk_add_f32 v[82:83], v[82:83], v[166:167]
	v_pk_add_f32 v[80:81], v[80:81], v[160:161]
	v_pk_add_f32 v[82:83], v[82:83], v[162:163]
	v_cndmask_b32_e64 v84, v84, v80, s[76:77]
	v_cndmask_b32_e64 v85, v85, v81, s[76:77]
	v_cndmask_b32_e64 v86, v86, v82, s[76:77]
	v_cndmask_b32_e64 v87, v87, v83, s[76:77]
	v_fma_f32 v224, v79, v84, -v220
	v_fma_f32 v225, v79, v85, -v221
	v_fma_f32 v226, v79, v86, -v222
	v_fma_f32 v227, v79, v87, -v223
	v_cvt_pk_bf16_f32 v230, v224, v225
	v_cvt_pk_bf16_f32 v231, v226, v227
	global_store_dwordx2 v89, v[230:231], s[24:25] offset:2048
	v_lshrrev_b32_e32 v38, 4, v246
